# band-skip attention plus: slot rotation/step counter moved before the step barrier, burst reads in the attention epilogue, all s_setprio removed
# speedup vs baseline: 1.0134x; 1.0061x over previous
.Lat_noresc_442:
	v_add_u32_e32 v3, s58, v244
	ds_read_b64_tr_b16 v[192:193], v250 offset:2048
	ds_read_b64_tr_b16 v[194:195], v250 offset:2560
	ds_read_b64_tr_b16 v[196:197], v250 offset:6144
	ds_read_b64_tr_b16 v[198:199], v250 offset:6656
	s_waitcnt lgkmcnt(4)
	v_mfma_f32_32x32x16_bf16 v[64:79], v[180:183], v[200:203], v[64:79]
	v_exp_f32_e32 v128, v128
	v_exp_f32_e32 v129, v129
	v_exp_f32_e32 v130, v130
	ds_read_b128 v[208:211], v3
	v_mfma_f32_32x32x16_bf16 v[80:95], v[180:183], v[204:207], v[80:95]
	v_exp_f32_e32 v131, v131
	v_exp_f32_e32 v132, v132
	v_exp_f32_e32 v133, v133
	ds_read_b128 v[212:215], v3 offset:512
	ds_read_b64_tr_b16 v[200:201], v250 offset:10240
	ds_read_b64_tr_b16 v[202:203], v250 offset:10752
	ds_read_b64_tr_b16 v[204:205], v250 offset:14336
	ds_read_b64_tr_b16 v[206:207], v250 offset:14848
	s_waitcnt lgkmcnt(6)
	v_mfma_f32_32x32x16_bf16 v[32:47], v[184:187], v[192:195], v[32:47]
	v_exp_f32_e32 v134, v134
	v_exp_f32_e32 v135, v135
	v_exp_f32_e32 v136, v136
	ds_read_b128 v[216:219], v3 offset:2048
	v_mfma_f32_32x32x16_bf16 v[48:63], v[184:187], v[196:199], v[48:63]
	v_exp_f32_e32 v137, v137
	v_exp_f32_e32 v138, v138
	v_exp_f32_e32 v139, v139
	ds_read_b128 v[220:223], v3 offset:2560
	ds_read_b64_tr_b16 v[192:193], v250 offset:3072
	ds_read_b64_tr_b16 v[194:195], v250 offset:3584
	ds_read_b64_tr_b16 v[196:197], v250 offset:7168
	ds_read_b64_tr_b16 v[198:199], v250 offset:7680
	s_waitcnt lgkmcnt(6)
	v_mfma_f32_32x32x16_bf16 v[64:79], v[184:187], v[200:203], v[64:79]
	v_exp_f32_e32 v140, v140
	v_exp_f32_e32 v141, v141
	v_exp_f32_e32 v142, v142
	ds_read_b128 v[224:227], v3 offset:4096
	v_mfma_f32_32x32x16_bf16 v[80:95], v[184:187], v[204:207], v[80:95]
	v_exp_f32_e32 v143, v143
	v_exp_f32_e32 v144, v144
	v_exp_f32_e32 v145, v145
	ds_read_b128 v[228:231], v3 offset:4608
	ds_read_b64_tr_b16 v[200:201], v250 offset:11264
	ds_read_b64_tr_b16 v[202:203], v250 offset:11776
	ds_read_b64_tr_b16 v[204:205], v250 offset:15360
	ds_read_b64_tr_b16 v[206:207], v250 offset:15872
	s_waitcnt lgkmcnt(6)
	v_mfma_f32_32x32x16_bf16 v[32:47], v[188:191], v[192:195], v[32:47]
	v_exp_f32_e32 v146, v146
	v_exp_f32_e32 v147, v147
	v_exp_f32_e32 v148, v148
	ds_read_b128 v[232:235], v3 offset:6144
	v_mfma_f32_32x32x16_bf16 v[48:63], v[188:191], v[196:199], v[48:63]
	v_exp_f32_e32 v149, v149
	v_exp_f32_e32 v150, v150
	v_exp_f32_e32 v151, v151
	ds_read_b128 v[240:243], v3 offset:6656
	s_waitcnt lgkmcnt(2)
	v_mfma_f32_32x32x16_bf16 v[64:79], v[188:191], v[200:203], v[64:79]
	v_exp_f32_e32 v152, v152
	v_exp_f32_e32 v153, v153
	v_exp_f32_e32 v154, v154
	v_exp_f32_e32 v155, v155
	v_mfma_f32_32x32x16_bf16 v[80:95], v[188:191], v[204:207], v[80:95]
	v_exp_f32_e32 v156, v156
	v_exp_f32_e32 v157, v157
	v_exp_f32_e32 v158, v158
	v_exp_f32_e32 v159, v159
	s_mov_b32 s67, s56
	s_mov_b32 s56, s57
	s_mov_b32 s57, s58
	s_mov_b32 s58, s67
	s_add_u32 s46, s46, 1
	s_waitcnt vmcnt(3) lgkmcnt(0)
	s_barrier
	s_cmp_lg_u64 s[68:69], 0
	s_cbranch_scc0 .Lat_norescO_442
	v_lshl_add_u32 v250, v252, 4, v249
	ds_read_b128 v[0:3], v250 offset:0
	ds_read_b128 v[4:7], v250 offset:32
	ds_read_b128 v[8:11], v250 offset:64
	ds_read_b128 v[12:15], v250 offset:96
	s_nop 7
	s_nop 7
	s_waitcnt lgkmcnt(0)
	v_mul_f32_e32 v32, v32, v0
	v_mul_f32_e32 v33, v33, v1
	v_mul_f32_e32 v34, v34, v2
	v_mul_f32_e32 v35, v35, v3
	v_mul_f32_e32 v36, v36, v4
	v_mul_f32_e32 v37, v37, v5
	v_mul_f32_e32 v38, v38, v6
	v_mul_f32_e32 v39, v39, v7
	v_mul_f32_e32 v40, v40, v8
	v_mul_f32_e32 v41, v41, v9
	v_mul_f32_e32 v42, v42, v10
	v_mul_f32_e32 v43, v43, v11
	v_mul_f32_e32 v44, v44, v12
	v_mul_f32_e32 v45, v45, v13
	v_mul_f32_e32 v46, v46, v14
	v_mul_f32_e32 v47, v47, v15
	v_mul_f32_e32 v48, v48, v0
	v_mul_f32_e32 v49, v49, v1
	v_mul_f32_e32 v50, v50, v2
	v_mul_f32_e32 v51, v51, v3
	v_mul_f32_e32 v52, v52, v4
	v_mul_f32_e32 v53, v53, v5
	v_mul_f32_e32 v54, v54, v6
	v_mul_f32_e32 v55, v55, v7
	v_mul_f32_e32 v56, v56, v8
	v_mul_f32_e32 v57, v57, v9
	v_mul_f32_e32 v58, v58, v10
	v_mul_f32_e32 v59, v59, v11
	v_mul_f32_e32 v60, v60, v12
	v_mul_f32_e32 v61, v61, v13
	v_mul_f32_e32 v62, v62, v14
	v_mul_f32_e32 v63, v63, v15
	v_mul_f32_e32 v64, v64, v0
	v_mul_f32_e32 v65, v65, v1
	v_mul_f32_e32 v66, v66, v2
	v_mul_f32_e32 v67, v67, v3
	v_mul_f32_e32 v68, v68, v4
	v_mul_f32_e32 v69, v69, v5
	v_mul_f32_e32 v70, v70, v6
	v_mul_f32_e32 v71, v71, v7
	v_mul_f32_e32 v72, v72, v8
	v_mul_f32_e32 v73, v73, v9
	v_mul_f32_e32 v74, v74, v10
	v_mul_f32_e32 v75, v75, v11
	v_mul_f32_e32 v76, v76, v12
	v_mul_f32_e32 v77, v77, v13
	v_mul_f32_e32 v78, v78, v14
	v_mul_f32_e32 v79, v79, v15
	v_mul_f32_e32 v80, v80, v0
	v_mul_f32_e32 v81, v81, v1
	v_mul_f32_e32 v82, v82, v2
	v_mul_f32_e32 v83, v83, v3
	v_mul_f32_e32 v84, v84, v4
	v_mul_f32_e32 v85, v85, v5
	v_mul_f32_e32 v86, v86, v6
	v_mul_f32_e32 v87, v87, v7
	v_mul_f32_e32 v88, v88, v8
	v_mul_f32_e32 v89, v89, v9
	v_mul_f32_e32 v90, v90, v10
	v_mul_f32_e32 v91, v91, v11
	v_mul_f32_e32 v92, v92, v12
	v_mul_f32_e32 v93, v93, v13
	v_mul_f32_e32 v94, v94, v14
	v_mul_f32_e32 v95, v95, v15
.Lat_norescO_442:
.Lat_next_442:
	s_cmp_ge_u32 s46, s45
	s_cbranch_scc1 .Lat_drain
	s_cmp_ge_u32 s46, s78
	s_cbranch_scc1 .Lat_lite_861
	s_lshl_b32 s60, s56, 1
	v_add_u32_e32 v250, s60, v245
	v_mfma_f32_32x32x16_bf16 v[96:111], v[208:211], v[16:19], v[160:175]
	v_add_f32_e32 v247, v247, v128
	v_add_f32_e32 v247, v247, v129
	v_add_f32_e32 v247, v247, v130
	v_add_f32_e32 v247, v247, v131
	v_cvt_pk_bf16_f32 v176, v128, v129
	v_cvt_pk_bf16_f32 v177, v130, v131
	v_mfma_f32_32x32x16_bf16 v[112:127], v[212:215], v[16:19], v[160:175]
	v_add_f32_e32 v247, v247, v132
	v_add_f32_e32 v247, v247, v133
	v_add_f32_e32 v247, v247, v134
	v_add_f32_e32 v247, v247, v135
	v_cvt_pk_bf16_f32 v178, v132, v133
	v_cvt_pk_bf16_f32 v179, v134, v135
	v_mfma_f32_32x32x16_bf16 v[96:111], v[216:219], v[20:23], v[96:111]
	v_add_f32_e32 v247, v247, v136
	v_add_f32_e32 v247, v247, v137
	v_add_f32_e32 v247, v247, v138
	v_add_f32_e32 v247, v247, v139
	v_cvt_pk_bf16_f32 v180, v136, v137
	v_cvt_pk_bf16_f32 v181, v138, v139
	v_mfma_f32_32x32x16_bf16 v[112:127], v[220:223], v[20:23], v[112:127]
	v_add_f32_e32 v247, v247, v140
	v_add_f32_e32 v247, v247, v141
	v_add_f32_e32 v247, v247, v142
	v_add_f32_e32 v247, v247, v143
	v_cvt_pk_bf16_f32 v182, v140, v141
	v_cvt_pk_bf16_f32 v183, v142, v143
	v_mfma_f32_32x32x16_bf16 v[96:111], v[224:227], v[24:27], v[96:111]
	v_add_f32_e32 v247, v247, v144
	v_add_f32_e32 v247, v247, v145
	v_add_f32_e32 v247, v247, v146
	v_add_f32_e32 v247, v247, v147
	v_cvt_pk_bf16_f32 v184, v144, v145
	v_cvt_pk_bf16_f32 v185, v146, v147
	v_mfma_f32_32x32x16_bf16 v[112:127], v[228:231], v[24:27], v[112:127]
	v_add_f32_e32 v247, v247, v148
	v_add_f32_e32 v247, v247, v149
	v_add_f32_e32 v247, v247, v150
	v_add_f32_e32 v247, v247, v151
	v_cvt_pk_bf16_f32 v186, v148, v149
	v_cvt_pk_bf16_f32 v187, v150, v151
	v_mfma_f32_32x32x16_bf16 v[96:111], v[232:235], v[28:31], v[96:111]
	v_add_f32_e32 v247, v247, v152
	v_add_f32_e32 v247, v247, v153
	v_add_f32_e32 v247, v247, v154
	v_add_f32_e32 v247, v247, v155
	v_cvt_pk_bf16_f32 v188, v152, v153
	v_cvt_pk_bf16_f32 v189, v154, v155
	ds_read_b64_tr_b16 v[192:193], v250 offset:0
	ds_read_b64_tr_b16 v[194:195], v250 offset:512
	v_mfma_f32_32x32x16_bf16 v[112:127], v[240:243], v[28:31], v[112:127]
	v_add_f32_e32 v247, v247, v156
	v_add_f32_e32 v247, v247, v157
	v_add_f32_e32 v247, v247, v158
	v_add_f32_e32 v247, v247, v159
	v_cvt_pk_bf16_f32 v190, v156, v157
	v_cvt_pk_bf16_f32 v191, v158, v159
	ds_read_b64_tr_b16 v[196:197], v250 offset:4096
	ds_read_b64_tr_b16 v[198:199], v250 offset:4608
	s_add_i32 m0, s57, s70
	s_nop 0
	global_load_lds_dwordx4 v238, s[74:75]
	s_add_u32 s74, s74, 0x10000
	s_addc_u32 s75, s75, 0
	s_lshl_b32 s60, s58, 1
	s_add_i32 s60, s60, s71
	s_mov_b32 m0, s60
	s_nop 0
	global_load_lds_dwordx4 v239, s[76:77]
	s_add_u32 s62, s76, 0x80
	s_addc_u32 s63, s77, 0
	s_add_i32 m0, s60, 0x2000
	s_nop 0
	global_load_lds_dwordx4 v239, s[62:63]
	s_add_u32 s76, s76, 0x10000
	s_addc_u32 s77, s77, 0
	s_cmp_lt_u32 s46, s72
	s_cbranch_scc1 .Lat_nomask_944
	s_sub_u32 s60, s46, s72
	s_lshl_b32 s60, s60, 6
	v_lshl_add_u32 v0, v252, 2, s60
	v_sub_u32_e32 v0, v246, v0
	v_mov_b32_e32 v1, 0xff800000
	v_cmp_gt_i32_e64 s[60:61], 0, v0
	v_cmp_gt_i32_e64 s[62:63], 32, v0
	v_cmp_gt_i32_e64 s[64:65], 1, v0
	v_cmp_gt_i32_e64 s[66:67], 33, v0
	v_cndmask_b32_e64 v96, v96, v1, s[60:61]
	v_cmp_gt_i32_e64 s[60:61], 2, v0
	v_cndmask_b32_e64 v112, v112, v1, s[62:63]
	v_cmp_gt_i32_e64 s[62:63], 34, v0
	v_cndmask_b32_e64 v97, v97, v1, s[64:65]
	v_cmp_gt_i32_e64 s[64:65], 3, v0
	v_cndmask_b32_e64 v113, v113, v1, s[66:67]
	v_cmp_gt_i32_e64 s[66:67], 35, v0
	v_cndmask_b32_e64 v98, v98, v1, s[60:61]
	v_cmp_gt_i32_e64 s[60:61], 8, v0
	v_cndmask_b32_e64 v114, v114, v1, s[62:63]
	v_cmp_gt_i32_e64 s[62:63], 40, v0
	v_cndmask_b32_e64 v99, v99, v1, s[64:65]
	v_cmp_gt_i32_e64 s[64:65], 9, v0
	v_cndmask_b32_e64 v115, v115, v1, s[66:67]
	v_cmp_gt_i32_e64 s[66:67], 41, v0
	v_cndmask_b32_e64 v100, v100, v1, s[60:61]
	v_cmp_gt_i32_e64 s[60:61], 10, v0
	v_cndmask_b32_e64 v116, v116, v1, s[62:63]
	v_cmp_gt_i32_e64 s[62:63], 42, v0
	v_cndmask_b32_e64 v101, v101, v1, s[64:65]
	v_cmp_gt_i32_e64 s[64:65], 11, v0
	v_cndmask_b32_e64 v117, v117, v1, s[66:67]
	v_cmp_gt_i32_e64 s[66:67], 43, v0
	v_cndmask_b32_e64 v102, v102, v1, s[60:61]
	v_cmp_gt_i32_e64 s[60:61], 16, v0
	v_cndmask_b32_e64 v118, v118, v1, s[62:63]
	v_cmp_gt_i32_e64 s[62:63], 48, v0
	v_cndmask_b32_e64 v103, v103, v1, s[64:65]
	v_cmp_gt_i32_e64 s[64:65], 17, v0
	v_cndmask_b32_e64 v119, v119, v1, s[66:67]
	v_cmp_gt_i32_e64 s[66:67], 49, v0
	v_cndmask_b32_e64 v104, v104, v1, s[60:61]
	v_cmp_gt_i32_e64 s[60:61], 18, v0
	v_cndmask_b32_e64 v120, v120, v1, s[62:63]
	v_cmp_gt_i32_e64 s[62:63], 50, v0
	v_cndmask_b32_e64 v105, v105, v1, s[64:65]
	v_cmp_gt_i32_e64 s[64:65], 19, v0
	v_cndmask_b32_e64 v121, v121, v1, s[66:67]
	v_cmp_gt_i32_e64 s[66:67], 51, v0
	v_cndmask_b32_e64 v106, v106, v1, s[60:61]
	v_cmp_gt_i32_e64 s[60:61], 24, v0
	v_cndmask_b32_e64 v122, v122, v1, s[62:63]
	v_cmp_gt_i32_e64 s[62:63], 56, v0
	v_cndmask_b32_e64 v107, v107, v1, s[64:65]
	v_cmp_gt_i32_e64 s[64:65], 25, v0
	v_cndmask_b32_e64 v123, v123, v1, s[66:67]
	v_cmp_gt_i32_e64 s[66:67], 57, v0
	v_cndmask_b32_e64 v108, v108, v1, s[60:61]
	v_cmp_gt_i32_e64 s[60:61], 26, v0
	v_cndmask_b32_e64 v124, v124, v1, s[62:63]
	v_cmp_gt_i32_e64 s[62:63], 58, v0
	v_cndmask_b32_e64 v109, v109, v1, s[64:65]
	v_cmp_gt_i32_e64 s[64:65], 27, v0
	v_cndmask_b32_e64 v125, v125, v1, s[66:67]
	v_cmp_gt_i32_e64 s[66:67], 59, v0
	v_cndmask_b32_e64 v110, v110, v1, s[60:61]
	s_nop 1
	v_cndmask_b32_e64 v126, v126, v1, s[62:63]
	v_cndmask_b32_e64 v111, v111, v1, s[64:65]
	v_cndmask_b32_e64 v127, v127, v1, s[66:67]

.Lat_noresc_861:
	v_add_u32_e32 v3, s58, v244
	ds_read_b64_tr_b16 v[192:193], v250 offset:2048
	ds_read_b64_tr_b16 v[194:195], v250 offset:2560
	ds_read_b64_tr_b16 v[196:197], v250 offset:6144
	ds_read_b64_tr_b16 v[198:199], v250 offset:6656
	s_waitcnt lgkmcnt(4)
	v_mfma_f32_32x32x16_bf16 v[64:79], v[180:183], v[200:203], v[64:79]
	v_exp_f32_e32 v96, v96
	v_exp_f32_e32 v97, v97
	v_exp_f32_e32 v98, v98
	ds_read_b128 v[208:211], v3
	v_mfma_f32_32x32x16_bf16 v[80:95], v[180:183], v[204:207], v[80:95]
	v_exp_f32_e32 v99, v99
	v_exp_f32_e32 v100, v100
	v_exp_f32_e32 v101, v101
	ds_read_b128 v[212:215], v3 offset:512
	ds_read_b64_tr_b16 v[200:201], v250 offset:10240
	ds_read_b64_tr_b16 v[202:203], v250 offset:10752
	ds_read_b64_tr_b16 v[204:205], v250 offset:14336
	ds_read_b64_tr_b16 v[206:207], v250 offset:14848
	s_waitcnt lgkmcnt(6)
	v_mfma_f32_32x32x16_bf16 v[32:47], v[184:187], v[192:195], v[32:47]
	v_exp_f32_e32 v102, v102
	v_exp_f32_e32 v103, v103
	v_exp_f32_e32 v104, v104
	ds_read_b128 v[216:219], v3 offset:2048
	v_mfma_f32_32x32x16_bf16 v[48:63], v[184:187], v[196:199], v[48:63]
	v_exp_f32_e32 v105, v105
	v_exp_f32_e32 v106, v106
	v_exp_f32_e32 v107, v107
	ds_read_b128 v[220:223], v3 offset:2560
	ds_read_b64_tr_b16 v[192:193], v250 offset:3072
	ds_read_b64_tr_b16 v[194:195], v250 offset:3584
	ds_read_b64_tr_b16 v[196:197], v250 offset:7168
	ds_read_b64_tr_b16 v[198:199], v250 offset:7680
	s_waitcnt lgkmcnt(6)
	v_mfma_f32_32x32x16_bf16 v[64:79], v[184:187], v[200:203], v[64:79]
	v_exp_f32_e32 v108, v108
	v_exp_f32_e32 v109, v109
	v_exp_f32_e32 v110, v110
	ds_read_b128 v[224:227], v3 offset:4096
	v_mfma_f32_32x32x16_bf16 v[80:95], v[184:187], v[204:207], v[80:95]
	v_exp_f32_e32 v111, v111
	v_exp_f32_e32 v112, v112
	v_exp_f32_e32 v113, v113
	ds_read_b128 v[228:231], v3 offset:4608
	ds_read_b64_tr_b16 v[200:201], v250 offset:11264
	ds_read_b64_tr_b16 v[202:203], v250 offset:11776
	ds_read_b64_tr_b16 v[204:205], v250 offset:15360
	ds_read_b64_tr_b16 v[206:207], v250 offset:15872
	s_waitcnt lgkmcnt(6)
	v_mfma_f32_32x32x16_bf16 v[32:47], v[188:191], v[192:195], v[32:47]
	v_exp_f32_e32 v114, v114
	v_exp_f32_e32 v115, v115
	v_exp_f32_e32 v116, v116
	ds_read_b128 v[232:235], v3 offset:6144
	v_mfma_f32_32x32x16_bf16 v[48:63], v[188:191], v[196:199], v[48:63]
	v_exp_f32_e32 v117, v117
	v_exp_f32_e32 v118, v118
	v_exp_f32_e32 v119, v119
	ds_read_b128 v[240:243], v3 offset:6656
	s_waitcnt lgkmcnt(2)
	v_mfma_f32_32x32x16_bf16 v[64:79], v[188:191], v[200:203], v[64:79]
	v_exp_f32_e32 v120, v120
	v_exp_f32_e32 v121, v121
	v_exp_f32_e32 v122, v122
	v_exp_f32_e32 v123, v123
	v_mfma_f32_32x32x16_bf16 v[80:95], v[188:191], v[204:207], v[80:95]
	v_exp_f32_e32 v124, v124
	v_exp_f32_e32 v125, v125
	v_exp_f32_e32 v126, v126
	v_exp_f32_e32 v127, v127
	s_mov_b32 s67, s56
	s_mov_b32 s56, s57
	s_mov_b32 s57, s58
	s_mov_b32 s58, s67
	s_add_u32 s46, s46, 1
	s_waitcnt vmcnt(3) lgkmcnt(0)
	s_barrier
	s_cmp_lg_u64 s[68:69], 0
	s_cbranch_scc0 .Lat_norescO_861
	v_lshl_add_u32 v250, v252, 4, v249
	ds_read_b128 v[0:3], v250 offset:0
	ds_read_b128 v[4:7], v250 offset:32
	ds_read_b128 v[8:11], v250 offset:64
	ds_read_b128 v[12:15], v250 offset:96
	s_nop 7
	s_nop 7
	s_waitcnt lgkmcnt(0)
	v_mul_f32_e32 v32, v32, v0
	v_mul_f32_e32 v33, v33, v1
	v_mul_f32_e32 v34, v34, v2
	v_mul_f32_e32 v35, v35, v3
	v_mul_f32_e32 v36, v36, v4
	v_mul_f32_e32 v37, v37, v5
	v_mul_f32_e32 v38, v38, v6
	v_mul_f32_e32 v39, v39, v7
	v_mul_f32_e32 v40, v40, v8
	v_mul_f32_e32 v41, v41, v9
	v_mul_f32_e32 v42, v42, v10
	v_mul_f32_e32 v43, v43, v11
	v_mul_f32_e32 v44, v44, v12
	v_mul_f32_e32 v45, v45, v13
	v_mul_f32_e32 v46, v46, v14
	v_mul_f32_e32 v47, v47, v15
	v_mul_f32_e32 v48, v48, v0
	v_mul_f32_e32 v49, v49, v1
	v_mul_f32_e32 v50, v50, v2
	v_mul_f32_e32 v51, v51, v3
	v_mul_f32_e32 v52, v52, v4
	v_mul_f32_e32 v53, v53, v5
	v_mul_f32_e32 v54, v54, v6
	v_mul_f32_e32 v55, v55, v7
	v_mul_f32_e32 v56, v56, v8
	v_mul_f32_e32 v57, v57, v9
	v_mul_f32_e32 v58, v58, v10
	v_mul_f32_e32 v59, v59, v11
	v_mul_f32_e32 v60, v60, v12
	v_mul_f32_e32 v61, v61, v13
	v_mul_f32_e32 v62, v62, v14
	v_mul_f32_e32 v63, v63, v15
	v_mul_f32_e32 v64, v64, v0
	v_mul_f32_e32 v65, v65, v1
	v_mul_f32_e32 v66, v66, v2
	v_mul_f32_e32 v67, v67, v3
	v_mul_f32_e32 v68, v68, v4
	v_mul_f32_e32 v69, v69, v5
	v_mul_f32_e32 v70, v70, v6
	v_mul_f32_e32 v71, v71, v7
	v_mul_f32_e32 v72, v72, v8
	v_mul_f32_e32 v73, v73, v9
	v_mul_f32_e32 v74, v74, v10
	v_mul_f32_e32 v75, v75, v11
	v_mul_f32_e32 v76, v76, v12
	v_mul_f32_e32 v77, v77, v13
	v_mul_f32_e32 v78, v78, v14
	v_mul_f32_e32 v79, v79, v15
	v_mul_f32_e32 v80, v80, v0
	v_mul_f32_e32 v81, v81, v1
	v_mul_f32_e32 v82, v82, v2
	v_mul_f32_e32 v83, v83, v3
	v_mul_f32_e32 v84, v84, v4
	v_mul_f32_e32 v85, v85, v5
	v_mul_f32_e32 v86, v86, v6
	v_mul_f32_e32 v87, v87, v7
	v_mul_f32_e32 v88, v88, v8
	v_mul_f32_e32 v89, v89, v9
	v_mul_f32_e32 v90, v90, v10
	v_mul_f32_e32 v91, v91, v11
	v_mul_f32_e32 v92, v92, v12
	v_mul_f32_e32 v93, v93, v13
	v_mul_f32_e32 v94, v94, v14
	v_mul_f32_e32 v95, v95, v15
.Lat_norescO_861:
.Lat_next_861:
	s_cmp_lt_u32 s46, s45
	s_cbranch_scc1 .Lat_loop
	s_branch .Lat_drain

.Lat_epi:
	v_mov_b32_e32 v250, v247
	v_mov_b32_e32 v251, v247
	s_nop 1
	v_permlane32_swap_b32_e32 v250, v251
	v_add_f32_e32 v250, v250, v251
	s_waitcnt vmcnt(0) lgkmcnt(0)
	s_barrier
	v_and_b32_e32 v244, 31, v237
	v_lshl_add_u32 v244, v244, 2, v249
	v_cmp_eq_u32_e32 vcc, 0, v252
	s_and_saveexec_b64 s[60:61], vcc
	ds_write_b32 v244, v250 offset:128
	s_or_b64 exec, exec, s[60:61]
	s_waitcnt lgkmcnt(0)
	v_lshl_add_u32 v250, v252, 4, v249
	ds_read_b128 v[0:3], v250 offset:128
	ds_read_b128 v[4:7], v250 offset:160
	ds_read_b128 v[8:11], v250 offset:192
	ds_read_b128 v[12:15], v250 offset:224
	s_waitcnt lgkmcnt(0)
	v_rcp_f32_e32 v0, v0
	v_rcp_f32_e32 v1, v1
	v_rcp_f32_e32 v2, v2
	v_rcp_f32_e32 v3, v3
	v_rcp_f32_e32 v4, v4
	v_rcp_f32_e32 v5, v5
	v_rcp_f32_e32 v6, v6
	v_rcp_f32_e32 v7, v7
	v_rcp_f32_e32 v8, v8
	v_rcp_f32_e32 v9, v9
	v_rcp_f32_e32 v10, v10
	v_rcp_f32_e32 v11, v11
	v_rcp_f32_e32 v12, v12
	v_rcp_f32_e32 v13, v13
	v_rcp_f32_e32 v14, v14
	v_rcp_f32_e32 v15, v15
	s_nop 7
	s_nop 7
	s_lshl_b32 s60, s47, 13
	v_and_b32_e32 v250, 31, v237
	v_lshlrev_b32_e32 v250, 1, v250
	v_add_u32_e32 v250, s60, v250
	v_lshlrev_b32_e32 v251, 10, v252
	v_add_u32_e32 v250, v250, v251
	v_mul_f32_e32 v251, v32, v0
	v_cvt_pk_bf16_f32 v251, v251, v251
	ds_write_b16 v250, v251 offset:0
	v_mul_f32_e32 v251, v48, v0
	v_cvt_pk_bf16_f32 v251, v251, v251
	ds_write_b16 v250, v251 offset:64
	v_mul_f32_e32 v251, v64, v0
	v_cvt_pk_bf16_f32 v251, v251, v251
	ds_write_b16 v250, v251 offset:128
	v_mul_f32_e32 v251, v80, v0
	v_cvt_pk_bf16_f32 v251, v251, v251
	ds_write_b16 v250, v251 offset:192
	v_mul_f32_e32 v251, v33, v1
	v_cvt_pk_bf16_f32 v251, v251, v251
	ds_write_b16 v250, v251 offset:256
	v_mul_f32_e32 v251, v49, v1
	v_cvt_pk_bf16_f32 v251, v251, v251
	ds_write_b16 v250, v251 offset:320
	v_mul_f32_e32 v251, v65, v1
	v_cvt_pk_bf16_f32 v251, v251, v251
	ds_write_b16 v250, v251 offset:384
	v_mul_f32_e32 v251, v81, v1
	v_cvt_pk_bf16_f32 v251, v251, v251
	ds_write_b16 v250, v251 offset:448
	v_mul_f32_e32 v251, v34, v2
	v_cvt_pk_bf16_f32 v251, v251, v251
	ds_write_b16 v250, v251 offset:512
	v_mul_f32_e32 v251, v50, v2
	v_cvt_pk_bf16_f32 v251, v251, v251
	ds_write_b16 v250, v251 offset:576
	v_mul_f32_e32 v251, v66, v2
	v_cvt_pk_bf16_f32 v251, v251, v251
	ds_write_b16 v250, v251 offset:640
	v_mul_f32_e32 v251, v82, v2
	v_cvt_pk_bf16_f32 v251, v251, v251
	ds_write_b16 v250, v251 offset:704
	v_mul_f32_e32 v251, v35, v3
	v_cvt_pk_bf16_f32 v251, v251, v251
	ds_write_b16 v250, v251 offset:768
	v_mul_f32_e32 v251, v51, v3
	v_cvt_pk_bf16_f32 v251, v251, v251
	ds_write_b16 v250, v251 offset:832
	v_mul_f32_e32 v251, v67, v3
	v_cvt_pk_bf16_f32 v251, v251, v251
	ds_write_b16 v250, v251 offset:896
	v_mul_f32_e32 v251, v83, v3
	v_cvt_pk_bf16_f32 v251, v251, v251
	ds_write_b16 v250, v251 offset:960
	v_mul_f32_e32 v251, v36, v4
	v_cvt_pk_bf16_f32 v251, v251, v251
	ds_write_b16 v250, v251 offset:2048
	v_mul_f32_e32 v251, v52, v4
	v_cvt_pk_bf16_f32 v251, v251, v251
	ds_write_b16 v250, v251 offset:2112
	v_mul_f32_e32 v251, v68, v4
	v_cvt_pk_bf16_f32 v251, v251, v251
	ds_write_b16 v250, v251 offset:2176
	v_mul_f32_e32 v251, v84, v4
	v_cvt_pk_bf16_f32 v251, v251, v251
	ds_write_b16 v250, v251 offset:2240
	v_mul_f32_e32 v251, v37, v5
	v_cvt_pk_bf16_f32 v251, v251, v251
	ds_write_b16 v250, v251 offset:2304
	v_mul_f32_e32 v251, v53, v5
	v_cvt_pk_bf16_f32 v251, v251, v251
	ds_write_b16 v250, v251 offset:2368
	v_mul_f32_e32 v251, v69, v5
	v_cvt_pk_bf16_f32 v251, v251, v251
	ds_write_b16 v250, v251 offset:2432
	v_mul_f32_e32 v251, v85, v5
	v_cvt_pk_bf16_f32 v251, v251, v251
	ds_write_b16 v250, v251 offset:2496
	v_mul_f32_e32 v251, v38, v6
	v_cvt_pk_bf16_f32 v251, v251, v251
	ds_write_b16 v250, v251 offset:2560
	v_mul_f32_e32 v251, v54, v6
	v_cvt_pk_bf16_f32 v251, v251, v251
	ds_write_b16 v250, v251 offset:2624
	v_mul_f32_e32 v251, v70, v6
	v_cvt_pk_bf16_f32 v251, v251, v251
	ds_write_b16 v250, v251 offset:2688
	v_mul_f32_e32 v251, v86, v6
	v_cvt_pk_bf16_f32 v251, v251, v251
	ds_write_b16 v250, v251 offset:2752
	v_mul_f32_e32 v251, v39, v7
	v_cvt_pk_bf16_f32 v251, v251, v251
	ds_write_b16 v250, v251 offset:2816
	v_mul_f32_e32 v251, v55, v7
	v_cvt_pk_bf16_f32 v251, v251, v251
	ds_write_b16 v250, v251 offset:2880
	v_mul_f32_e32 v251, v71, v7
	v_cvt_pk_bf16_f32 v251, v251, v251
	ds_write_b16 v250, v251 offset:2944
	v_mul_f32_e32 v251, v87, v7
	v_cvt_pk_bf16_f32 v251, v251, v251
	ds_write_b16 v250, v251 offset:3008
	v_mul_f32_e32 v251, v40, v8
	v_cvt_pk_bf16_f32 v251, v251, v251
	ds_write_b16 v250, v251 offset:4096
	v_mul_f32_e32 v251, v56, v8
	v_cvt_pk_bf16_f32 v251, v251, v251
	ds_write_b16 v250, v251 offset:4160
	v_mul_f32_e32 v251, v72, v8
	v_cvt_pk_bf16_f32 v251, v251, v251
	ds_write_b16 v250, v251 offset:4224
	v_mul_f32_e32 v251, v88, v8
	v_cvt_pk_bf16_f32 v251, v251, v251
	ds_write_b16 v250, v251 offset:4288
	v_mul_f32_e32 v251, v41, v9
	v_cvt_pk_bf16_f32 v251, v251, v251
	ds_write_b16 v250, v251 offset:4352
	v_mul_f32_e32 v251, v57, v9
	v_cvt_pk_bf16_f32 v251, v251, v251
	ds_write_b16 v250, v251 offset:4416
	v_mul_f32_e32 v251, v73, v9
	v_cvt_pk_bf16_f32 v251, v251, v251
	ds_write_b16 v250, v251 offset:4480
	v_mul_f32_e32 v251, v89, v9
	v_cvt_pk_bf16_f32 v251, v251, v251
	ds_write_b16 v250, v251 offset:4544
	v_mul_f32_e32 v251, v42, v10
	v_cvt_pk_bf16_f32 v251, v251, v251
	ds_write_b16 v250, v251 offset:4608
	v_mul_f32_e32 v251, v58, v10
	v_cvt_pk_bf16_f32 v251, v251, v251
	ds_write_b16 v250, v251 offset:4672
	v_mul_f32_e32 v251, v74, v10
	v_cvt_pk_bf16_f32 v251, v251, v251
	ds_write_b16 v250, v251 offset:4736
	v_mul_f32_e32 v251, v90, v10
	v_cvt_pk_bf16_f32 v251, v251, v251
	ds_write_b16 v250, v251 offset:4800
	v_mul_f32_e32 v251, v43, v11
	v_cvt_pk_bf16_f32 v251, v251, v251
	ds_write_b16 v250, v251 offset:4864
	v_mul_f32_e32 v251, v59, v11
	v_cvt_pk_bf16_f32 v251, v251, v251
	ds_write_b16 v250, v251 offset:4928
	v_mul_f32_e32 v251, v75, v11
	v_cvt_pk_bf16_f32 v251, v251, v251
	ds_write_b16 v250, v251 offset:4992
	v_mul_f32_e32 v251, v91, v11
	v_cvt_pk_bf16_f32 v251, v251, v251
	ds_write_b16 v250, v251 offset:5056
	v_mul_f32_e32 v251, v44, v12
	v_cvt_pk_bf16_f32 v251, v251, v251
	ds_write_b16 v250, v251 offset:6144
	v_mul_f32_e32 v251, v60, v12
	v_cvt_pk_bf16_f32 v251, v251, v251
	ds_write_b16 v250, v251 offset:6208
	v_mul_f32_e32 v251, v76, v12
	v_cvt_pk_bf16_f32 v251, v251, v251
	ds_write_b16 v250, v251 offset:6272
	v_mul_f32_e32 v251, v92, v12
	v_cvt_pk_bf16_f32 v251, v251, v251
	ds_write_b16 v250, v251 offset:6336
	v_mul_f32_e32 v251, v45, v13
	v_cvt_pk_bf16_f32 v251, v251, v251
	ds_write_b16 v250, v251 offset:6400
	v_mul_f32_e32 v251, v61, v13
	v_cvt_pk_bf16_f32 v251, v251, v251
	ds_write_b16 v250, v251 offset:6464
	v_mul_f32_e32 v251, v77, v13
	v_cvt_pk_bf16_f32 v251, v251, v251
	ds_write_b16 v250, v251 offset:6528
	v_mul_f32_e32 v251, v93, v13
	v_cvt_pk_bf16_f32 v251, v251, v251
	ds_write_b16 v250, v251 offset:6592
	v_mul_f32_e32 v251, v46, v14
	v_cvt_pk_bf16_f32 v251, v251, v251
	ds_write_b16 v250, v251 offset:6656
	v_mul_f32_e32 v251, v62, v14
	v_cvt_pk_bf16_f32 v251, v251, v251
	ds_write_b16 v250, v251 offset:6720
	v_mul_f32_e32 v251, v78, v14
	v_cvt_pk_bf16_f32 v251, v251, v251
	ds_write_b16 v250, v251 offset:6784
	v_mul_f32_e32 v251, v94, v14
	v_cvt_pk_bf16_f32 v251, v251, v251
	ds_write_b16 v250, v251 offset:6848
	v_mul_f32_e32 v251, v47, v15
	v_cvt_pk_bf16_f32 v251, v251, v251
	ds_write_b16 v250, v251 offset:6912
	v_mul_f32_e32 v251, v63, v15
	v_cvt_pk_bf16_f32 v251, v251, v251
	ds_write_b16 v250, v251 offset:6976
	v_mul_f32_e32 v251, v79, v15
	v_cvt_pk_bf16_f32 v251, v251, v251
	ds_write_b16 v250, v251 offset:7040
	v_mul_f32_e32 v251, v95, v15
	v_cvt_pk_bf16_f32 v251, v251, v251
	ds_write_b16 v250, v251 offset:7104
	s_waitcnt lgkmcnt(0)
	v_lshrrev_b32_e32 v251, 4, v237
	v_and_b32_e32 v244, 15, v237
	v_lshlrev_b32_e32 v245, 8, v251
	v_lshl_or_b32 v245, v244, 4, v245
	v_add_u32_e32 v245, s60, v245
	v_lshlrev_b32_e32 v246, 11, v251
	v_lshl_or_b32 v246, v244, 4, v246
	ds_read_b128 v[16:19], v245 offset:0
	ds_read_b128 v[20:23], v245 offset:1024
	ds_read_b128 v[24:27], v245 offset:2048
	ds_read_b128 v[28:31], v245 offset:3072
	ds_read_b128 v[0:3], v245 offset:4096
	ds_read_b128 v[4:7], v245 offset:5120
	ds_read_b128 v[8:11], v245 offset:6144
	ds_read_b128 v[12:15], v245 offset:7168
	s_waitcnt lgkmcnt(7)
	global_store_dwordx4 v246, v[16:19], s[52:53]
	v_add_u32_e32 v246, 0x2000, v246
	s_waitcnt lgkmcnt(6)
	global_store_dwordx4 v246, v[20:23], s[52:53]
	v_add_u32_e32 v246, 0x2000, v246
	s_waitcnt lgkmcnt(5)
	global_store_dwordx4 v246, v[24:27], s[52:53]
	v_add_u32_e32 v246, 0x2000, v246
	s_waitcnt lgkmcnt(4)
	global_store_dwordx4 v246, v[28:31], s[52:53]
	v_add_u32_e32 v246, 0x2000, v246
	s_waitcnt lgkmcnt(3)
	global_store_dwordx4 v246, v[0:3], s[52:53]
	v_add_u32_e32 v246, 0x2000, v246
	s_waitcnt lgkmcnt(2)
	global_store_dwordx4 v246, v[4:7], s[52:53]
	v_add_u32_e32 v246, 0x2000, v246
	s_waitcnt lgkmcnt(1)
	global_store_dwordx4 v246, v[8:11], s[52:53]
	v_add_u32_e32 v246, 0x2000, v246
	s_waitcnt lgkmcnt(0)
	global_store_dwordx4 v246, v[12:15], s[52:53]
	s_waitcnt lgkmcnt(0)
	s_barrier
